# M_MIX non-rotary epilogue: 8 rs loads hoisted
# speedup vs baseline: 1.0070x; 1.0070x over previous
; __device__ __forceinline__ float sigm_f(float v) { return __builtin_amdgcn_rcpf(1.0f + __builtin_amdgcn_exp2f(-1.44269504f * v)); }
; __device__ __forceinline__ float silu_f(float v) { return v * sigm_f(v); }
;     __device__ __forceinline__ void operator()(const f32x4 (&acc)[2][2][4][2], const Unit& u, int wr, int wc, int fr, int fq) const {
;     ...
;                 for (int ai = 0; ai < 2; ++ai)
; #pragma unroll
;                     for (int m = 0; m < 4; ++m) { const int row = row0 + ai * HALF + m * 16; const float rsv = __builtin_amdgcn_rsqf(rs[row] * (1.0f / 1024.0f) + 1e-6f);
;                         bf16_t* rowp = O + (size_t)row * ldc + u.pn * BM + cw;
; #pragma unroll
;                         for (int bj = 0; bj < 2; ++bj) { f32x4 v0 = acc[ai][bj][m][0] * rsv, v1 = acc[ai][bj][m][1] * rsv;
;                             if (sub == 1) {
; #pragma unroll
;                                 for (int e = 0; e < 4; ++e) { v0[e] = silu_f(v0[e]); v1[e] = silu_f(v1[e]); } }
;                             else if (sub == 3) {
; #pragma unroll
;                                 for (int e = 0; e < 4; ++e) { v0[e] = sigm_f(v0[e]); v1[e] = sigm_f(v1[e]); } }
;                             store8(rowp + bj * HALF, v0, v1); } }
.LBB0_486:
	s_andn2_b64 vcc, exec, s[6:7]
	s_cbranch_vccnz .LBB0_587
	v_ashrrev_i32_e32 v165, 31, v164
	v_lshl_add_u64 v[128:129], v[164:165], 2, s[26:27]
	global_load_dword v130, v[128:129], off
	global_load_dword v247, v[128:129], off offset:64
	global_load_dword v248, v[128:129], off offset:128
	global_load_dword v249, v[128:129], off offset:192
	global_load_dword v250, v[128:129], off offset:512
	global_load_dword v252, v[128:129], off offset:576
	global_load_dword v253, v[128:129], off offset:640
	global_load_dword v255, v[128:129], off offset:704
	s_lshl_b32 s62, s40, 8
	s_cmp_lt_i32 s40, 4
	s_mov_b64 s[6:7], -1
	s_waitcnt vmcnt(0) lgkmcnt(0)
	v_fmamk_f32 v130, v130, 0x3a800000, v237
	v_rsq_f32_e32 v130, v130
	s_cbranch_scc1 .LBB0_585
	s_cmp_lt_u32 s40, 12
	s_cselect_b32 s6, 2, 3
	s_cmp_gt_u32 s40, 7
	s_cselect_b32 s38, s6, 1
	v_pk_mul_f32 v[132:133], v[126:127], v[130:131] op_sel_hi:[1,0]
	v_pk_mul_f32 v[134:135], v[124:125], v[130:131] op_sel_hi:[1,0]
	v_pk_mul_f32 v[136:137], v[122:123], v[130:131] op_sel_hi:[1,0]
	v_pk_mul_f32 v[138:139], v[120:121], v[130:131] op_sel_hi:[1,0]
	s_cmp_gt_i32 s38, 2
	s_mov_b64 s[6:7], -1
	s_cbranch_scc0 .LBB0_490
	v_mul_f32_e32 v131, 0xbfb8aa3b, v134
	v_exp_f32_e32 v131, v131
	v_mul_f32_e32 v165, 0xbfb8aa3b, v138
	v_exp_f32_e32 v165, v165
	v_mul_f32_e32 v167, 0xbfb8aa3b, v139
	v_add_f32_e32 v131, 1.0, v131
	v_exp_f32_e32 v168, v167
	v_add_f32_e32 v166, 1.0, v165
	v_rcp_f32_e32 v165, v131
	v_mul_f32_e32 v131, 0xbfb8aa3b, v135
	v_exp_f32_e32 v131, v131
	v_rcp_f32_e32 v166, v166
	s_mov_b64 s[6:7], 0
	v_add_f32_e32 v131, 1.0, v131
	v_rcp_f32_e32 v167, v131
	v_add_f32_e32 v131, 1.0, v168
	v_mul_f32_e32 v168, 0xbfb8aa3b, v132
	v_exp_f32_e32 v169, v168
	v_mul_f32_e32 v168, 0xbfb8aa3b, v136
	v_exp_f32_e32 v170, v168
	v_rcp_f32_e32 v168, v131
	v_add_f32_e32 v131, 1.0, v169
	v_rcp_f32_e32 v169, v131
	v_add_f32_e32 v131, 1.0, v170
	v_mul_f32_e32 v170, 0xbfb8aa3b, v133
	v_exp_f32_e32 v171, v170
	v_mul_f32_e32 v170, 0xbfb8aa3b, v137
	v_exp_f32_e32 v173, v170
	v_rcp_f32_e32 v170, v131
	v_add_f32_e32 v131, 1.0, v171
	v_rcp_f32_e32 v172, v131
	v_add_f32_e32 v131, 1.0, v173
	v_rcp_f32_e32 v171, v131

; __device__ __forceinline__ float sigm_f(float v) { return __builtin_amdgcn_rcpf(1.0f + __builtin_amdgcn_exp2f(-1.44269504f * v)); }
; __device__ __forceinline__ float silu_f(float v) { return v * sigm_f(v); }
;     __device__ __forceinline__ void operator()(const f32x4 (&acc)[2][2][4][2], const Unit& u, int wr, int wc, int fr, int fq) const {
;     ...
;                 for (int ai = 0; ai < 2; ++ai)
; #pragma unroll
;                     for (int m = 0; m < 4; ++m) { const int row = row0 + ai * HALF + m * 16; const float rsv = __builtin_amdgcn_rsqf(rs[row] * (1.0f / 1024.0f) + 1e-6f);
;                         bf16_t* rowp = O + (size_t)row * ldc + u.pn * BM + cw;
; #pragma unroll
;                         for (int bj = 0; bj < 2; ++bj) { f32x4 v0 = acc[ai][bj][m][0] * rsv, v1 = acc[ai][bj][m][1] * rsv;
;                             if (sub == 1) {
; #pragma unroll
;                                 for (int e = 0; e < 4; ++e) { v0[e] = silu_f(v0[e]); v1[e] = silu_f(v1[e]); } }
;                             else if (sub == 3) {
; #pragma unroll
;                                 for (int e = 0; e < 4; ++e) { v0[e] = sigm_f(v0[e]); v1[e] = sigm_f(v1[e]); } }
;                             store8(rowp + bj * HALF, v0, v1); } }
.LBB0_500:
	v_cvt_pk_bf16_f32 v134, v131, v168
	v_cvt_pk_bf16_f32 v135, v170, v173
	v_cvt_pk_bf16_f32 v136, v165, v169
	v_cvt_pk_bf16_f32 v137, v171, v172
	flat_store_dwordx4 v[132:133], v[134:137] offset:256
	s_cmp_gt_i32 s38, 2
	s_mov_b64 s[6:7], -1
	v_fmamk_f32 v131, v247, 0x3a800000, v237
	v_rsq_f32_e32 v132, v131
	s_nop 0
	v_pk_mul_f32 v[136:137], v[118:119], v[132:133] op_sel_hi:[1,0]
	v_pk_mul_f32 v[166:167], v[116:117], v[132:133] op_sel_hi:[1,0]
	v_pk_mul_f32 v[134:135], v[114:115], v[132:133] op_sel_hi:[1,0]
	v_pk_mul_f32 v[138:139], v[112:113], v[132:133] op_sel_hi:[1,0]
	s_cbranch_scc0 .LBB0_502
	v_mul_f32_e32 v133, 0xbfb8aa3b, v138
	v_exp_f32_e32 v133, v133
	v_mul_f32_e32 v165, 0xbfb8aa3b, v167
	v_exp_f32_e32 v168, v165
	v_mul_f32_e32 v165, 0xbfb8aa3b, v139
	v_exp_f32_e32 v169, v165
	v_add_f32_e32 v133, 1.0, v133
	v_rcp_f32_e32 v165, v133
	v_add_f32_e32 v133, 1.0, v168
	v_rcp_f32_e32 v168, v133
	v_add_f32_e32 v133, 1.0, v169
	v_mul_f32_e32 v169, 0xbfb8aa3b, v136
	v_exp_f32_e32 v170, v169
	v_mul_f32_e32 v169, 0xbfb8aa3b, v134
	v_exp_f32_e32 v171, v169
	v_rcp_f32_e32 v169, v133
	v_add_f32_e32 v133, 1.0, v170
	v_rcp_f32_e32 v170, v133
	v_add_f32_e32 v133, 1.0, v171
	v_mul_f32_e32 v171, 0xbfb8aa3b, v137
	v_mul_f32_e32 v131, 0xbfb8aa3b, v166
	v_exp_f32_e32 v172, v171
	v_mul_f32_e32 v171, 0xbfb8aa3b, v135
	v_exp_f32_e32 v131, v131
	v_exp_f32_e32 v174, v171
	v_rcp_f32_e32 v171, v133
	v_add_f32_e32 v133, 1.0, v172
	v_add_f32_e32 v131, 1.0, v131
	v_rcp_f32_e32 v173, v133
	v_add_f32_e32 v133, 1.0, v174
	v_rcp_f32_e32 v131, v131
	v_rcp_f32_e32 v172, v133
	s_mov_b64 s[6:7], 0

; __device__ __forceinline__ float sigm_f(float v) { return __builtin_amdgcn_rcpf(1.0f + __builtin_amdgcn_exp2f(-1.44269504f * v)); }
; __device__ __forceinline__ float silu_f(float v) { return v * sigm_f(v); }
;     __device__ __forceinline__ void operator()(const f32x4 (&acc)[2][2][4][2], const Unit& u, int wr, int wc, int fr, int fq) const {
;     ...
;                 for (int ai = 0; ai < 2; ++ai)
; #pragma unroll
;                     for (int m = 0; m < 4; ++m) { const int row = row0 + ai * HALF + m * 16; const float rsv = __builtin_amdgcn_rsqf(rs[row] * (1.0f / 1024.0f) + 1e-6f);
;                         bf16_t* rowp = O + (size_t)row * ldc + u.pn * BM + cw;
; #pragma unroll
;                         for (int bj = 0; bj < 2; ++bj) { f32x4 v0 = acc[ai][bj][m][0] * rsv, v1 = acc[ai][bj][m][1] * rsv;
;                             if (sub == 1) {
; #pragma unroll
;                                 for (int e = 0; e < 4; ++e) { v0[e] = silu_f(v0[e]); v1[e] = silu_f(v1[e]); } }
;                             else if (sub == 3) {
; #pragma unroll
;                                 for (int e = 0; e < 4; ++e) { v0[e] = sigm_f(v0[e]); v1[e] = sigm_f(v1[e]); } }
;                             store8(rowp + bj * HALF, v0, v1); } }
.LBB0_512:
	v_cvt_pk_bf16_f32 v136, v131, v168
	v_cvt_pk_bf16_f32 v137, v170, v173
	v_cvt_pk_bf16_f32 v138, v165, v169
	v_cvt_pk_bf16_f32 v139, v171, v172
	flat_store_dwordx4 v[134:135], v[136:139] offset:256
	s_cmp_gt_i32 s38, 2
	s_mov_b64 s[6:7], -1
	v_fmamk_f32 v131, v248, 0x3a800000, v237
	v_rsq_f32_e32 v132, v131
	s_nop 0
	v_pk_mul_f32 v[136:137], v[102:103], v[132:133] op_sel_hi:[1,0]
	v_pk_mul_f32 v[166:167], v[100:101], v[132:133] op_sel_hi:[1,0]
	v_pk_mul_f32 v[134:135], v[98:99], v[132:133] op_sel_hi:[1,0]
	v_pk_mul_f32 v[138:139], v[96:97], v[132:133] op_sel_hi:[1,0]
	s_cbranch_scc0 .LBB0_514
	v_mul_f32_e32 v133, 0xbfb8aa3b, v138
	v_exp_f32_e32 v133, v133
	v_mul_f32_e32 v165, 0xbfb8aa3b, v167
	v_exp_f32_e32 v168, v165
	v_mul_f32_e32 v165, 0xbfb8aa3b, v139
	v_exp_f32_e32 v169, v165
	v_add_f32_e32 v133, 1.0, v133
	v_rcp_f32_e32 v165, v133
	v_add_f32_e32 v133, 1.0, v168
	v_rcp_f32_e32 v168, v133
	v_add_f32_e32 v133, 1.0, v169
	v_mul_f32_e32 v169, 0xbfb8aa3b, v136
	v_exp_f32_e32 v170, v169
	v_mul_f32_e32 v169, 0xbfb8aa3b, v134
	v_exp_f32_e32 v171, v169
	v_rcp_f32_e32 v169, v133
	v_add_f32_e32 v133, 1.0, v170
	v_rcp_f32_e32 v170, v133
	v_add_f32_e32 v133, 1.0, v171
	v_mul_f32_e32 v171, 0xbfb8aa3b, v137
	v_mul_f32_e32 v131, 0xbfb8aa3b, v166
	v_exp_f32_e32 v172, v171
	v_mul_f32_e32 v171, 0xbfb8aa3b, v135
	v_exp_f32_e32 v131, v131
	v_exp_f32_e32 v174, v171
	v_rcp_f32_e32 v171, v133
	v_add_f32_e32 v133, 1.0, v172
	v_add_f32_e32 v131, 1.0, v131
	v_rcp_f32_e32 v173, v133
	v_add_f32_e32 v133, 1.0, v174
	v_rcp_f32_e32 v131, v131
	v_rcp_f32_e32 v172, v133
	s_mov_b64 s[6:7], 0

; __device__ __forceinline__ float sigm_f(float v) { return __builtin_amdgcn_rcpf(1.0f + __builtin_amdgcn_exp2f(-1.44269504f * v)); }
; __device__ __forceinline__ float silu_f(float v) { return v * sigm_f(v); }
;     __device__ __forceinline__ void operator()(const f32x4 (&acc)[2][2][4][2], const Unit& u, int wr, int wc, int fr, int fq) const {
;     ...
;                 for (int ai = 0; ai < 2; ++ai)
; #pragma unroll
;                     for (int m = 0; m < 4; ++m) { const int row = row0 + ai * HALF + m * 16; const float rsv = __builtin_amdgcn_rsqf(rs[row] * (1.0f / 1024.0f) + 1e-6f);
;                         bf16_t* rowp = O + (size_t)row * ldc + u.pn * BM + cw;
; #pragma unroll
;                         for (int bj = 0; bj < 2; ++bj) { f32x4 v0 = acc[ai][bj][m][0] * rsv, v1 = acc[ai][bj][m][1] * rsv;
;                             if (sub == 1) {
; #pragma unroll
;                                 for (int e = 0; e < 4; ++e) { v0[e] = silu_f(v0[e]); v1[e] = silu_f(v1[e]); } }
;                             else if (sub == 3) {
; #pragma unroll
;                                 for (int e = 0; e < 4; ++e) { v0[e] = sigm_f(v0[e]); v1[e] = sigm_f(v1[e]); } }
;                             store8(rowp + bj * HALF, v0, v1); } }
.LBB0_524:
	v_cvt_pk_bf16_f32 v136, v131, v168
	v_cvt_pk_bf16_f32 v137, v170, v173
	v_cvt_pk_bf16_f32 v138, v165, v169
	v_cvt_pk_bf16_f32 v139, v171, v172
	flat_store_dwordx4 v[134:135], v[136:139] offset:256
	s_cmp_gt_i32 s38, 2
	s_mov_b64 s[6:7], -1
	v_fmamk_f32 v131, v249, 0x3a800000, v237
	v_rsq_f32_e32 v132, v131
	s_nop 0
	v_pk_mul_f32 v[136:137], v[86:87], v[132:133] op_sel_hi:[1,0]
	v_pk_mul_f32 v[166:167], v[84:85], v[132:133] op_sel_hi:[1,0]
	v_pk_mul_f32 v[134:135], v[82:83], v[132:133] op_sel_hi:[1,0]
	v_pk_mul_f32 v[138:139], v[80:81], v[132:133] op_sel_hi:[1,0]
	s_cbranch_scc0 .LBB0_526
	v_mul_f32_e32 v133, 0xbfb8aa3b, v138
	v_exp_f32_e32 v133, v133
	v_mul_f32_e32 v165, 0xbfb8aa3b, v167
	v_exp_f32_e32 v168, v165
	v_mul_f32_e32 v165, 0xbfb8aa3b, v139
	v_exp_f32_e32 v169, v165
	v_add_f32_e32 v133, 1.0, v133
	v_rcp_f32_e32 v165, v133
	v_add_f32_e32 v133, 1.0, v168
	v_rcp_f32_e32 v168, v133
	v_add_f32_e32 v133, 1.0, v169
	v_mul_f32_e32 v169, 0xbfb8aa3b, v136
	v_exp_f32_e32 v170, v169
	v_mul_f32_e32 v169, 0xbfb8aa3b, v134
	v_exp_f32_e32 v171, v169
	v_rcp_f32_e32 v169, v133
	v_add_f32_e32 v133, 1.0, v170
	v_rcp_f32_e32 v170, v133
	v_add_f32_e32 v133, 1.0, v171
	v_mul_f32_e32 v171, 0xbfb8aa3b, v137
	v_mul_f32_e32 v131, 0xbfb8aa3b, v166
	v_exp_f32_e32 v172, v171
	v_mul_f32_e32 v171, 0xbfb8aa3b, v135
	v_exp_f32_e32 v131, v131
	v_exp_f32_e32 v174, v171
	v_rcp_f32_e32 v171, v133
	v_add_f32_e32 v133, 1.0, v172
	v_add_f32_e32 v131, 1.0, v131
	v_rcp_f32_e32 v173, v133
	v_add_f32_e32 v133, 1.0, v174
	v_rcp_f32_e32 v131, v131
	v_rcp_f32_e32 v172, v133
	s_mov_b64 s[6:7], 0

; __device__ __forceinline__ float sigm_f(float v) { return __builtin_amdgcn_rcpf(1.0f + __builtin_amdgcn_exp2f(-1.44269504f * v)); }
; __device__ __forceinline__ float silu_f(float v) { return v * sigm_f(v); }
;     __device__ __forceinline__ void operator()(const f32x4 (&acc)[2][2][4][2], const Unit& u, int wr, int wc, int fr, int fq) const {
;     ...
;                 for (int ai = 0; ai < 2; ++ai)
; #pragma unroll
;                     for (int m = 0; m < 4; ++m) { const int row = row0 + ai * HALF + m * 16; const float rsv = __builtin_amdgcn_rsqf(rs[row] * (1.0f / 1024.0f) + 1e-6f);
;                         bf16_t* rowp = O + (size_t)row * ldc + u.pn * BM + cw;
; #pragma unroll
;                         for (int bj = 0; bj < 2; ++bj) { f32x4 v0 = acc[ai][bj][m][0] * rsv, v1 = acc[ai][bj][m][1] * rsv;
;                             if (sub == 1) {
; #pragma unroll
;                                 for (int e = 0; e < 4; ++e) { v0[e] = silu_f(v0[e]); v1[e] = silu_f(v1[e]); } }
;                             else if (sub == 3) {
; #pragma unroll
;                                 for (int e = 0; e < 4; ++e) { v0[e] = sigm_f(v0[e]); v1[e] = sigm_f(v1[e]); } }
;                             store8(rowp + bj * HALF, v0, v1); } }
.LBB0_536:
	v_cvt_pk_bf16_f32 v136, v131, v168
	v_cvt_pk_bf16_f32 v137, v170, v173
	v_cvt_pk_bf16_f32 v138, v165, v169
	v_cvt_pk_bf16_f32 v139, v171, v172
	flat_store_dwordx4 v[134:135], v[136:139] offset:256
	s_cmp_gt_i32 s38, 2
	s_mov_b64 s[6:7], -1
	v_fmamk_f32 v131, v250, 0x3a800000, v237
	v_rsq_f32_e32 v132, v131
	s_nop 0
	v_pk_mul_f32 v[136:137], v[62:63], v[132:133] op_sel_hi:[1,0]
	v_pk_mul_f32 v[166:167], v[60:61], v[132:133] op_sel_hi:[1,0]
	v_pk_mul_f32 v[134:135], v[58:59], v[132:133] op_sel_hi:[1,0]
	v_pk_mul_f32 v[138:139], v[56:57], v[132:133] op_sel_hi:[1,0]
	s_cbranch_scc0 .LBB0_538
	v_mul_f32_e32 v133, 0xbfb8aa3b, v138
	v_exp_f32_e32 v133, v133
	v_mul_f32_e32 v165, 0xbfb8aa3b, v167
	v_exp_f32_e32 v168, v165
	v_mul_f32_e32 v165, 0xbfb8aa3b, v139
	v_exp_f32_e32 v169, v165
	v_add_f32_e32 v133, 1.0, v133
	v_rcp_f32_e32 v165, v133
	v_add_f32_e32 v133, 1.0, v168
	v_rcp_f32_e32 v168, v133
	v_add_f32_e32 v133, 1.0, v169
	v_mul_f32_e32 v169, 0xbfb8aa3b, v136
	v_exp_f32_e32 v170, v169
	v_mul_f32_e32 v169, 0xbfb8aa3b, v134
	v_exp_f32_e32 v171, v169
	v_rcp_f32_e32 v169, v133
	v_add_f32_e32 v133, 1.0, v170
	v_rcp_f32_e32 v170, v133
	v_add_f32_e32 v133, 1.0, v171
	v_mul_f32_e32 v171, 0xbfb8aa3b, v137
	v_mul_f32_e32 v131, 0xbfb8aa3b, v166
	v_exp_f32_e32 v172, v171
	v_mul_f32_e32 v171, 0xbfb8aa3b, v135
	v_exp_f32_e32 v131, v131
	v_exp_f32_e32 v174, v171
	v_rcp_f32_e32 v171, v133
	v_add_f32_e32 v133, 1.0, v172
	v_add_f32_e32 v131, 1.0, v131
	v_rcp_f32_e32 v173, v133
	v_add_f32_e32 v133, 1.0, v174
	v_rcp_f32_e32 v131, v131
	v_rcp_f32_e32 v172, v133
	s_mov_b64 s[6:7], 0

; __device__ __forceinline__ float sigm_f(float v) { return __builtin_amdgcn_rcpf(1.0f + __builtin_amdgcn_exp2f(-1.44269504f * v)); }
; __device__ __forceinline__ float silu_f(float v) { return v * sigm_f(v); }
;     __device__ __forceinline__ void operator()(const f32x4 (&acc)[2][2][4][2], const Unit& u, int wr, int wc, int fr, int fq) const {
;     ...
;                 for (int ai = 0; ai < 2; ++ai)
; #pragma unroll
;                     for (int m = 0; m < 4; ++m) { const int row = row0 + ai * HALF + m * 16; const float rsv = __builtin_amdgcn_rsqf(rs[row] * (1.0f / 1024.0f) + 1e-6f);
;                         bf16_t* rowp = O + (size_t)row * ldc + u.pn * BM + cw;
; #pragma unroll
;                         for (int bj = 0; bj < 2; ++bj) { f32x4 v0 = acc[ai][bj][m][0] * rsv, v1 = acc[ai][bj][m][1] * rsv;
;                             if (sub == 1) {
; #pragma unroll
;                                 for (int e = 0; e < 4; ++e) { v0[e] = silu_f(v0[e]); v1[e] = silu_f(v1[e]); } }
;                             else if (sub == 3) {
; #pragma unroll
;                                 for (int e = 0; e < 4; ++e) { v0[e] = sigm_f(v0[e]); v1[e] = sigm_f(v1[e]); } }
;                             store8(rowp + bj * HALF, v0, v1); } }
.LBB0_548:
	v_cvt_pk_bf16_f32 v136, v131, v168
	v_cvt_pk_bf16_f32 v137, v170, v173
	v_cvt_pk_bf16_f32 v138, v165, v169
	v_cvt_pk_bf16_f32 v139, v171, v172
	flat_store_dwordx4 v[134:135], v[136:139] offset:256
	s_cmp_gt_i32 s38, 2
	s_mov_b64 s[6:7], -1
	v_fmamk_f32 v131, v252, 0x3a800000, v237
	v_rsq_f32_e32 v132, v131
	s_nop 0
	v_pk_mul_f32 v[136:137], v[54:55], v[132:133] op_sel_hi:[1,0]
	v_pk_mul_f32 v[166:167], v[52:53], v[132:133] op_sel_hi:[1,0]
	v_pk_mul_f32 v[134:135], v[50:51], v[132:133] op_sel_hi:[1,0]
	v_pk_mul_f32 v[138:139], v[48:49], v[132:133] op_sel_hi:[1,0]
	s_cbranch_scc0 .LBB0_550
	v_mul_f32_e32 v133, 0xbfb8aa3b, v138
	v_exp_f32_e32 v133, v133
	v_mul_f32_e32 v165, 0xbfb8aa3b, v167
	v_exp_f32_e32 v168, v165
	v_mul_f32_e32 v165, 0xbfb8aa3b, v139
	v_exp_f32_e32 v169, v165
	v_add_f32_e32 v133, 1.0, v133
	v_rcp_f32_e32 v165, v133
	v_add_f32_e32 v133, 1.0, v168
	v_rcp_f32_e32 v168, v133
	v_add_f32_e32 v133, 1.0, v169
	v_mul_f32_e32 v169, 0xbfb8aa3b, v136
	v_exp_f32_e32 v170, v169
	v_mul_f32_e32 v169, 0xbfb8aa3b, v134
	v_exp_f32_e32 v171, v169
	v_rcp_f32_e32 v169, v133
	v_add_f32_e32 v133, 1.0, v170
	v_rcp_f32_e32 v170, v133
	v_add_f32_e32 v133, 1.0, v171
	v_mul_f32_e32 v171, 0xbfb8aa3b, v137
	v_mul_f32_e32 v131, 0xbfb8aa3b, v166
	v_exp_f32_e32 v172, v171
	v_mul_f32_e32 v171, 0xbfb8aa3b, v135
	v_exp_f32_e32 v131, v131
	v_exp_f32_e32 v174, v171
	v_rcp_f32_e32 v171, v133
	v_add_f32_e32 v133, 1.0, v172
	v_add_f32_e32 v131, 1.0, v131
	v_rcp_f32_e32 v173, v133
	v_add_f32_e32 v133, 1.0, v174
	v_rcp_f32_e32 v131, v131
	v_rcp_f32_e32 v172, v133
	s_mov_b64 s[6:7], 0

; __device__ __forceinline__ float sigm_f(float v) { return __builtin_amdgcn_rcpf(1.0f + __builtin_amdgcn_exp2f(-1.44269504f * v)); }
; __device__ __forceinline__ float silu_f(float v) { return v * sigm_f(v); }
;     __device__ __forceinline__ void operator()(const f32x4 (&acc)[2][2][4][2], const Unit& u, int wr, int wc, int fr, int fq) const {
;     ...
;                 for (int ai = 0; ai < 2; ++ai)
; #pragma unroll
;                     for (int m = 0; m < 4; ++m) { const int row = row0 + ai * HALF + m * 16; const float rsv = __builtin_amdgcn_rsqf(rs[row] * (1.0f / 1024.0f) + 1e-6f);
;                         bf16_t* rowp = O + (size_t)row * ldc + u.pn * BM + cw;
; #pragma unroll
;                         for (int bj = 0; bj < 2; ++bj) { f32x4 v0 = acc[ai][bj][m][0] * rsv, v1 = acc[ai][bj][m][1] * rsv;
;                             if (sub == 1) {
; #pragma unroll
;                                 for (int e = 0; e < 4; ++e) { v0[e] = silu_f(v0[e]); v1[e] = silu_f(v1[e]); } }
;                             else if (sub == 3) {
; #pragma unroll
;                                 for (int e = 0; e < 4; ++e) { v0[e] = sigm_f(v0[e]); v1[e] = sigm_f(v1[e]); } }
;                             store8(rowp + bj * HALF, v0, v1); } }
.LBB0_560:
	v_cvt_pk_bf16_f32 v136, v131, v168
	v_cvt_pk_bf16_f32 v137, v170, v173
	v_cvt_pk_bf16_f32 v138, v165, v169
	v_cvt_pk_bf16_f32 v139, v171, v172
	flat_store_dwordx4 v[134:135], v[136:139] offset:256
	s_cmp_gt_i32 s38, 2
	s_mov_b64 s[6:7], -1
	v_fmamk_f32 v131, v253, 0x3a800000, v237
	v_rsq_f32_e32 v132, v131
	s_nop 0
	v_pk_mul_f32 v[136:137], v[38:39], v[132:133] op_sel_hi:[1,0]
	v_pk_mul_f32 v[166:167], v[36:37], v[132:133] op_sel_hi:[1,0]
	v_pk_mul_f32 v[134:135], v[34:35], v[132:133] op_sel_hi:[1,0]
	v_pk_mul_f32 v[138:139], v[32:33], v[132:133] op_sel_hi:[1,0]
	s_cbranch_scc0 .LBB0_562
	v_mul_f32_e32 v133, 0xbfb8aa3b, v138
	v_exp_f32_e32 v133, v133
	v_mul_f32_e32 v165, 0xbfb8aa3b, v167
	v_exp_f32_e32 v168, v165
	v_mul_f32_e32 v165, 0xbfb8aa3b, v139
	v_exp_f32_e32 v169, v165
	v_add_f32_e32 v133, 1.0, v133
	v_rcp_f32_e32 v165, v133
	v_add_f32_e32 v133, 1.0, v168
	v_rcp_f32_e32 v168, v133
	v_add_f32_e32 v133, 1.0, v169
	v_mul_f32_e32 v169, 0xbfb8aa3b, v136
	v_exp_f32_e32 v170, v169
	v_mul_f32_e32 v169, 0xbfb8aa3b, v134
	v_exp_f32_e32 v171, v169
	v_rcp_f32_e32 v169, v133
	v_add_f32_e32 v133, 1.0, v170
	v_rcp_f32_e32 v170, v133
	v_add_f32_e32 v133, 1.0, v171
	v_mul_f32_e32 v171, 0xbfb8aa3b, v137
	v_mul_f32_e32 v131, 0xbfb8aa3b, v166
	v_exp_f32_e32 v172, v171
	v_mul_f32_e32 v171, 0xbfb8aa3b, v135
	v_exp_f32_e32 v131, v131
	v_exp_f32_e32 v174, v171
	v_rcp_f32_e32 v171, v133
	v_add_f32_e32 v133, 1.0, v172
	v_add_f32_e32 v131, 1.0, v131
	v_rcp_f32_e32 v173, v133
	v_add_f32_e32 v133, 1.0, v174
	v_rcp_f32_e32 v131, v131
	v_rcp_f32_e32 v172, v133
	s_mov_b64 s[6:7], 0

; __device__ __forceinline__ float sigm_f(float v) { return __builtin_amdgcn_rcpf(1.0f + __builtin_amdgcn_exp2f(-1.44269504f * v)); }
; __device__ __forceinline__ float silu_f(float v) { return v * sigm_f(v); }
;     __device__ __forceinline__ void operator()(const f32x4 (&acc)[2][2][4][2], const Unit& u, int wr, int wc, int fr, int fq) const {
;     ...
;                 for (int ai = 0; ai < 2; ++ai)
; #pragma unroll
;                     for (int m = 0; m < 4; ++m) { const int row = row0 + ai * HALF + m * 16; const float rsv = __builtin_amdgcn_rsqf(rs[row] * (1.0f / 1024.0f) + 1e-6f);
;                         bf16_t* rowp = O + (size_t)row * ldc + u.pn * BM + cw;
; #pragma unroll
;                         for (int bj = 0; bj < 2; ++bj) { f32x4 v0 = acc[ai][bj][m][0] * rsv, v1 = acc[ai][bj][m][1] * rsv;
;                             if (sub == 1) {
; #pragma unroll
;                                 for (int e = 0; e < 4; ++e) { v0[e] = silu_f(v0[e]); v1[e] = silu_f(v1[e]); } }
;                             else if (sub == 3) {
; #pragma unroll
;                                 for (int e = 0; e < 4; ++e) { v0[e] = sigm_f(v0[e]); v1[e] = sigm_f(v1[e]); } }
;                             store8(rowp + bj * HALF, v0, v1); } }
.LBB0_572:
	v_cvt_pk_bf16_f32 v136, v131, v168
	v_cvt_pk_bf16_f32 v137, v170, v173
	v_cvt_pk_bf16_f32 v138, v165, v169
	v_cvt_pk_bf16_f32 v139, v171, v172
	flat_store_dwordx4 v[134:135], v[136:139] offset:256
	s_cmp_gt_i32 s38, 2
	s_mov_b64 s[6:7], -1
	v_fmamk_f32 v131, v255, 0x3a800000, v237
	v_rsq_f32_e32 v132, v131
	s_nop 0
	v_pk_mul_f32 v[136:137], v[22:23], v[132:133] op_sel_hi:[1,0]
	v_pk_mul_f32 v[166:167], v[20:21], v[132:133] op_sel_hi:[1,0]
	v_pk_mul_f32 v[134:135], v[18:19], v[132:133] op_sel_hi:[1,0]
	v_pk_mul_f32 v[138:139], v[16:17], v[132:133] op_sel_hi:[1,0]
	s_cbranch_scc0 .LBB0_574
	v_mul_f32_e32 v133, 0xbfb8aa3b, v138
	v_exp_f32_e32 v133, v133
	v_mul_f32_e32 v165, 0xbfb8aa3b, v167
	v_exp_f32_e32 v168, v165
	v_mul_f32_e32 v165, 0xbfb8aa3b, v139
	v_exp_f32_e32 v169, v165
	v_add_f32_e32 v133, 1.0, v133
	v_rcp_f32_e32 v165, v133
	v_add_f32_e32 v133, 1.0, v168
	v_rcp_f32_e32 v168, v133
	v_add_f32_e32 v133, 1.0, v169
	v_mul_f32_e32 v169, 0xbfb8aa3b, v136
	v_exp_f32_e32 v170, v169
	v_mul_f32_e32 v169, 0xbfb8aa3b, v134
	v_exp_f32_e32 v171, v169
	v_rcp_f32_e32 v169, v133
	v_add_f32_e32 v133, 1.0, v170
	v_rcp_f32_e32 v170, v133
	v_add_f32_e32 v133, 1.0, v171
	v_mul_f32_e32 v171, 0xbfb8aa3b, v137
	v_mul_f32_e32 v131, 0xbfb8aa3b, v166
	v_exp_f32_e32 v172, v171
	v_mul_f32_e32 v171, 0xbfb8aa3b, v135
	v_exp_f32_e32 v131, v131
	v_exp_f32_e32 v174, v171
	v_rcp_f32_e32 v171, v133
	v_add_f32_e32 v133, 1.0, v172
	v_add_f32_e32 v131, 1.0, v131
	v_rcp_f32_e32 v173, v133
	v_add_f32_e32 v133, 1.0, v174
	v_rcp_f32_e32 v131, v131
	v_rcp_f32_e32 v172, v133
	s_mov_b64 s[6:7], 0
